# v89 + barrier entry: kernarg barrier-pointer s_load hoisted above the workgroup s_barrier (off the arrival critical path)
# speedup vs baseline: 1.0008x; 1.0008x over previous
.LBB0_10:
.LBB0_11:
	s_mov_b64 s[16:17], s[0:1]
	s_getreg_b32 s6, hwreg(HW_REG_XCC_ID, 0, 4)
	s_load_dwordx2 s[4:5], s[16:17], 0xd0
	s_waitcnt vmcnt(0)
	v_mov_b32_e32 v1, v0
	s_barrier
	s_nop 0
	v_cmp_eq_u32_e32 vcc, 0, v1
	s_and_saveexec_b64 s[2:3], vcc
	s_cbranch_execz .LBB0_63
	v_mov_b32_e32 v1, 0x20ff0
	s_waitcnt vmcnt(0) expcnt(0) lgkmcnt(0)
	ds_read_b32 v3, v1
	v_mov_b32_e32 v1, 0x20ff4
	ds_read_b32 v1, v1
	s_and_b32 s11, s6, 15
	s_waitcnt lgkmcnt(1)
	v_cmp_ne_u32_e32 vcc, 0, v3
	s_cbranch_vccnz .LBB0_27
	s_load_dwordx2 s[14:15], s[0:1], 0xe0
	s_load_dword s13, s[0:1], 0xe8
	s_add_u32 s6, s4, 0x1000
	s_addc_u32 s7, s5, 0
	s_add_u32 s12, s4, 0x1100
	s_waitcnt lgkmcnt(0)
	s_mul_i32 s28, s15, s14
	s_mul_i32 s28, s28, s13
	s_addc_u32 s13, s5, 0
	s_add_u32 s14, s4, 0x1200
	s_addc_u32 s15, s5, 0
	s_add_u32 s20, s4, 0x1300
	s_addc_u32 s21, s5, 0
	s_mov_b32 s29, 1
	v_mov_b32_e32 v17, 0
	s_branch .LBB0_15

.LBB0_162:
.LBB0_163:
	s_getreg_b32 s8, hwreg(HW_REG_XCC_ID, 0, 4)
	s_load_dwordx2 s[6:7], s[16:17], 0xd0
	s_waitcnt vmcnt(0)
	v_mov_b32_e32 v1, v0
	s_waitcnt lgkmcnt(0)
	s_barrier
	s_nop 0
	v_cmp_eq_u32_e32 vcc, 0, v1
	s_and_saveexec_b64 s[2:3], vcc
	s_cbranch_execz .LBB0_215
	v_mov_b32_e32 v1, 0x20ff0
	s_waitcnt vmcnt(0) expcnt(0) lgkmcnt(0)
	ds_read_b32 v3, v1
	v_mov_b32_e32 v1, 0x20ff4
	ds_read_b32 v1, v1
	s_and_b32 s11, s8, 15
	s_waitcnt lgkmcnt(1)
	v_cmp_ne_u32_e32 vcc, 0, v3
	s_cbranch_vccnz .LBB0_179
	s_load_dwordx2 s[14:15], s[0:1], 0xe0
	s_load_dword s13, s[0:1], 0xe8
	s_add_u32 s8, s6, 0x1000
	s_addc_u32 s9, s7, 0
	s_add_u32 s12, s6, 0x1100
	s_waitcnt lgkmcnt(0)
	s_mul_i32 s28, s15, s14
	s_mul_i32 s28, s28, s13
	s_addc_u32 s13, s7, 0
	s_add_u32 s14, s6, 0x1200
	s_addc_u32 s15, s7, 0
	s_add_u32 s20, s6, 0x1300
	s_addc_u32 s21, s7, 0
	s_mov_b32 s29, 1
	v_mov_b32_e32 v17, 0
	s_branch .LBB0_167

.LBB0_227:
.LBB0_228:
	s_getreg_b32 s8, hwreg(HW_REG_XCC_ID, 0, 4)
	s_load_dwordx2 s[4:5], s[16:17], 0xd0
	s_waitcnt vmcnt(0)
	v_mov_b32_e32 v1, v0
	s_waitcnt lgkmcnt(0)
	s_barrier
	s_nop 0
	v_cmp_eq_u32_e32 vcc, 0, v1
	s_and_saveexec_b64 s[2:3], vcc
	s_cbranch_execz .LBB0_280
	v_mov_b32_e32 v1, 0x20ff0
	s_waitcnt vmcnt(0) expcnt(0) lgkmcnt(0)
	ds_read_b32 v3, v1
	v_mov_b32_e32 v1, 0x20ff4
	ds_read_b32 v1, v1
	s_and_b32 s11, s8, 15
	s_waitcnt lgkmcnt(1)
	v_cmp_ne_u32_e32 vcc, 0, v3
	s_cbranch_vccnz .LBB0_244
	s_load_dwordx2 s[14:15], s[0:1], 0xe0
	s_load_dword s13, s[0:1], 0xe8
	s_add_u32 s8, s4, 0x1000
	s_addc_u32 s9, s5, 0
	s_add_u32 s12, s4, 0x1100
	s_waitcnt lgkmcnt(0)
	s_mul_i32 s28, s15, s14
	s_mul_i32 s28, s28, s13
	s_addc_u32 s13, s5, 0
	s_add_u32 s14, s4, 0x1200
	s_addc_u32 s15, s5, 0
	s_add_u32 s20, s4, 0x1300
	s_addc_u32 s21, s5, 0
	s_mov_b32 s29, 1
	v_mov_b32_e32 v17, 0
	s_branch .LBB0_232

.LBB0_364:
.LBB0_365:
	s_getreg_b32 s6, hwreg(HW_REG_XCC_ID, 0, 4)
	s_load_dwordx2 s[4:5], s[16:17], 0xd0
	s_waitcnt vmcnt(0)
	v_mov_b32_e32 v1, v0
	s_waitcnt lgkmcnt(0)
	s_barrier
	s_nop 0
	v_cmp_eq_u32_e32 vcc, 0, v1
	s_and_saveexec_b64 s[2:3], vcc
	s_cbranch_execz .LBB0_417
	v_mov_b32_e32 v1, 0x20ff0
	s_waitcnt vmcnt(0) expcnt(0) lgkmcnt(0)
	ds_read_b32 v3, v1
	v_mov_b32_e32 v1, 0x20ff4
	ds_read_b32 v1, v1
	s_and_b32 s11, s6, 15
	s_waitcnt lgkmcnt(1)
	v_cmp_ne_u32_e32 vcc, 0, v3
	s_cbranch_vccnz .LBB0_381
	s_load_dwordx2 s[12:13], s[0:1], 0xe0
	s_load_dword s9, s[0:1], 0xe8
	s_add_u32 s6, s4, 0x1000
	s_addc_u32 s7, s5, 0
	s_add_u32 s8, s4, 0x1100
	s_waitcnt lgkmcnt(0)
	s_mul_i32 s28, s13, s12
	s_mul_i32 s28, s28, s9
	s_addc_u32 s9, s5, 0
	s_add_u32 s12, s4, 0x1200
	s_addc_u32 s13, s5, 0
	s_add_u32 s14, s4, 0x1300
	s_addc_u32 s15, s5, 0
	s_mov_b32 s29, 1
	v_mov_b32_e32 v17, 0
	s_branch .LBB0_369

.LBB0_439:
.LBB0_440:
	s_getreg_b32 s6, hwreg(HW_REG_XCC_ID, 0, 4)
	s_load_dwordx2 s[4:5], s[16:17], 0xd0
	s_waitcnt vmcnt(0)
	v_mov_b32_e32 v1, v0
	s_waitcnt lgkmcnt(0)
	s_barrier
	s_nop 0
	v_cmp_eq_u32_e32 vcc, 0, v1
	s_and_saveexec_b64 s[2:3], vcc
	s_cbranch_execz .LBB0_492
	v_mov_b32_e32 v1, 0x20ff0
	s_waitcnt vmcnt(0) expcnt(0) lgkmcnt(0)
	ds_read_b32 v3, v1
	v_mov_b32_e32 v1, 0x20ff4
	ds_read_b32 v1, v1
	s_and_b32 s11, s6, 15
	s_waitcnt lgkmcnt(1)
	v_cmp_ne_u32_e32 vcc, 0, v3
	s_cbranch_vccnz .LBB0_456
	s_load_dwordx2 s[14:15], s[0:1], 0xe0
	s_load_dword s13, s[0:1], 0xe8
	s_add_u32 s6, s4, 0x1000
	s_addc_u32 s7, s5, 0
	s_add_u32 s12, s4, 0x1100
	s_waitcnt lgkmcnt(0)
	s_mul_i32 s28, s15, s14
	s_mul_i32 s28, s28, s13
	s_addc_u32 s13, s5, 0
	s_add_u32 s14, s4, 0x1200
	s_addc_u32 s15, s5, 0
	s_add_u32 s20, s4, 0x1300
	s_addc_u32 s21, s5, 0
	s_mov_b32 s29, 1
	v_mov_b32_e32 v17, 0
	s_branch .LBB0_444

.LBB0_720:
.LBB0_721:
	s_getreg_b32 s6, hwreg(HW_REG_XCC_ID, 0, 4)
	s_load_dwordx2 s[4:5], s[16:17], 0xd0
	s_waitcnt vmcnt(0)
	v_mov_b32_e32 v1, v0
	s_waitcnt vmcnt(63) expcnt(7) lgkmcnt(15)
	s_barrier
	s_nop 0
	v_cmp_eq_u32_e32 vcc, 0, v1
	s_and_saveexec_b64 s[2:3], vcc
	s_cbranch_execz .LBB0_773
	v_mov_b32_e32 v1, 0x20ff0
	s_waitcnt vmcnt(0) expcnt(0) lgkmcnt(0)
	ds_read_b32 v3, v1
	v_mov_b32_e32 v1, 0x20ff4
	ds_read_b32 v1, v1
	s_and_b32 s11, s6, 15
	s_waitcnt lgkmcnt(1)
	v_cmp_ne_u32_e32 vcc, 0, v3
	s_cbranch_vccnz .LBB0_737
	s_load_dwordx2 s[12:13], s[0:1], 0xe0
	s_load_dword s9, s[0:1], 0xe8
	s_add_u32 s6, s4, 0x1000
	s_addc_u32 s7, s5, 0
	s_add_u32 s8, s4, 0x1100
	s_waitcnt lgkmcnt(0)
	s_mul_i32 s28, s13, s12
	s_mul_i32 s28, s28, s9
	s_addc_u32 s9, s5, 0
	s_add_u32 s12, s4, 0x1200
	s_addc_u32 s13, s5, 0
	s_add_u32 s14, s4, 0x1300
	s_addc_u32 s15, s5, 0
	s_mov_b32 s29, 1
	v_mov_b32_e32 v17, 0
	s_branch .LBB0_725

.LBB0_902:
.LBB0_903:
	s_getreg_b32 s6, hwreg(HW_REG_XCC_ID, 0, 4)
	s_load_dwordx2 s[4:5], s[16:17], 0xd0
	s_waitcnt vmcnt(0)
	v_mov_b32_e32 v1, v0
	s_waitcnt vmcnt(63) expcnt(7) lgkmcnt(15)
	s_barrier
	s_nop 0
	v_cmp_eq_u32_e32 vcc, 0, v1
	s_and_saveexec_b64 s[2:3], vcc
	s_cbranch_execz .LBB0_955
	v_mov_b32_e32 v1, 0x20ff0
	s_waitcnt vmcnt(0) expcnt(0) lgkmcnt(0)
	ds_read_b32 v3, v1
	v_mov_b32_e32 v1, 0x20ff4
	ds_read_b32 v1, v1
	s_and_b32 s11, s6, 15
	s_waitcnt lgkmcnt(1)
	v_cmp_ne_u32_e32 vcc, 0, v3
	s_cbranch_vccnz .LBB0_919
	s_load_dwordx2 s[14:15], s[0:1], 0xe0
	s_load_dword s13, s[0:1], 0xe8
	s_add_u32 s6, s4, 0x1000
	s_addc_u32 s7, s5, 0
	s_add_u32 s12, s4, 0x1100
	s_waitcnt lgkmcnt(0)
	s_mul_i32 s28, s15, s14
	s_mul_i32 s28, s28, s13
	s_addc_u32 s13, s5, 0
	s_add_u32 s14, s4, 0x1200
	s_addc_u32 s15, s5, 0
	s_add_u32 s20, s4, 0x1300
	s_addc_u32 s21, s5, 0
	s_mov_b32 s29, 1
	v_mov_b32_e32 v17, 0
	s_branch .LBB0_907

.LBB0_1023:
.LBB0_1024:
	s_getreg_b32 s6, hwreg(HW_REG_XCC_ID, 0, 4)
	s_load_dwordx2 s[4:5], s[16:17], 0xd0
	s_waitcnt vmcnt(0)
	v_mov_b32_e32 v1, v0
	s_waitcnt vmcnt(63) expcnt(7) lgkmcnt(15)
	s_barrier
	s_nop 0
	v_cmp_eq_u32_e32 vcc, 0, v1
	s_and_saveexec_b64 s[2:3], vcc
	s_cbranch_execz .LBB0_1076
	v_mov_b32_e32 v1, 0x20ff0
	s_waitcnt vmcnt(0) expcnt(0) lgkmcnt(0)
	ds_read_b32 v3, v1
	v_mov_b32_e32 v1, 0x20ff4
	ds_read_b32 v1, v1
	s_and_b32 s11, s6, 15
	s_waitcnt lgkmcnt(1)
	v_cmp_ne_u32_e32 vcc, 0, v3
	s_cbranch_vccnz .LBB0_1040
	s_load_dwordx2 s[14:15], s[0:1], 0xe0
	s_load_dword s9, s[0:1], 0xe8
	s_add_u32 s6, s4, 0x1000
	s_addc_u32 s7, s5, 0
	s_add_u32 s8, s4, 0x1100
	s_waitcnt lgkmcnt(0)
	s_mul_i32 s28, s15, s14
	s_mul_i32 s28, s28, s9
	s_addc_u32 s9, s5, 0
	s_add_u32 s14, s4, 0x1200
	s_addc_u32 s15, s5, 0
	s_add_u32 s20, s4, 0x1300
	s_addc_u32 s21, s5, 0
	s_mov_b32 s29, 1
	v_mov_b32_e32 v17, 0
	s_branch .LBB0_1028

.LBB0_1084:
.LBB0_1085:
	s_getreg_b32 s8, hwreg(HW_REG_XCC_ID, 0, 4)
	s_load_dwordx2 s[6:7], s[16:17], 0xd0
	s_waitcnt vmcnt(0)
	v_mov_b32_e32 v1, v0
	s_waitcnt vmcnt(63) expcnt(7) lgkmcnt(15)
	s_barrier
	s_nop 0
	v_cmp_eq_u32_e32 vcc, 0, v1
	s_and_saveexec_b64 s[2:3], vcc
	s_cbranch_execz .LBB0_1137
	v_mov_b32_e32 v1, 0x20ff0
	s_waitcnt vmcnt(0) expcnt(0) lgkmcnt(0)
	ds_read_b32 v3, v1
	v_mov_b32_e32 v1, 0x20ff4
	ds_read_b32 v1, v1
	s_and_b32 s11, s8, 15
	s_waitcnt lgkmcnt(1)
	v_cmp_ne_u32_e32 vcc, 0, v3
	s_cbranch_vccnz .LBB0_1101
	s_load_dwordx2 s[14:15], s[0:1], 0xe0
	s_load_dword s13, s[0:1], 0xe8
	s_add_u32 s8, s6, 0x1000
	s_addc_u32 s9, s7, 0
	s_add_u32 s12, s6, 0x1100
	s_waitcnt lgkmcnt(0)
	s_mul_i32 s28, s15, s14
	s_mul_i32 s28, s28, s13
	s_addc_u32 s13, s7, 0
	s_add_u32 s14, s6, 0x1200
	s_addc_u32 s15, s7, 0
	s_add_u32 s20, s6, 0x1300
	s_addc_u32 s21, s7, 0
	s_mov_b32 s29, 1
	v_mov_b32_e32 v17, 0
	s_branch .LBB0_1089

.LBB0_1470:
.LBB0_1471:
	s_getreg_b32 s8, hwreg(HW_REG_XCC_ID, 0, 4)
	s_load_dwordx2 s[4:5], s[16:17], 0xd0
	s_waitcnt vmcnt(0)
	v_mov_b32_e32 v1, v0
	s_waitcnt vmcnt(63) expcnt(7) lgkmcnt(15)
	s_barrier
	s_nop 0
	v_cmp_eq_u32_e32 vcc, 0, v1
	s_and_saveexec_b64 s[2:3], vcc
	s_cbranch_execz .LBB0_1523
	v_mov_b32_e32 v1, 0x20ff0
	s_waitcnt vmcnt(0) expcnt(0) lgkmcnt(0)
	ds_read_b32 v3, v1
	v_mov_b32_e32 v1, 0x20ff4
	ds_read_b32 v1, v1
	s_and_b32 s11, s8, 15
	s_waitcnt lgkmcnt(1)
	v_cmp_ne_u32_e32 vcc, 0, v3
	s_cbranch_vccnz .LBB0_1487
	s_load_dwordx2 s[14:15], s[0:1], 0xe0
	s_load_dword s13, s[0:1], 0xe8
	s_add_u32 s8, s4, 0x1000
	s_addc_u32 s9, s5, 0
	s_add_u32 s12, s4, 0x1100
	s_waitcnt lgkmcnt(0)
	s_mul_i32 s28, s15, s14
	s_mul_i32 s28, s28, s13
	s_addc_u32 s13, s5, 0
	s_add_u32 s14, s4, 0x1200
	s_addc_u32 s15, s5, 0
	s_add_u32 s20, s4, 0x1300
	s_addc_u32 s21, s5, 0
	s_mov_b32 s29, 1
	v_mov_b32_e32 v17, 0
	s_branch .LBB0_1475

.LBB0_2487:
.LBB0_2488:
	s_getreg_b32 s6, hwreg(HW_REG_XCC_ID, 0, 4)
	s_load_dwordx2 s[4:5], s[16:17], 0xd0
	s_waitcnt vmcnt(0)
	v_mov_b32_e32 v1, v0
	s_waitcnt vmcnt(63) expcnt(7) lgkmcnt(15)
	s_barrier
	s_nop 0
	v_cmp_eq_u32_e32 vcc, 0, v1
	s_and_saveexec_b64 s[2:3], vcc
	s_cbranch_execz .LBB0_2540
	v_mov_b32_e32 v1, 0x20ff0
	s_waitcnt vmcnt(0) expcnt(0) lgkmcnt(0)
	ds_read_b32 v3, v1
	v_mov_b32_e32 v1, 0x20ff4
	ds_read_b32 v1, v1
	s_and_b32 s11, s6, 15
	s_waitcnt lgkmcnt(1)
	v_cmp_ne_u32_e32 vcc, 0, v3
	s_cbranch_vccnz .LBB0_2504
	s_load_dwordx2 s[12:13], s[0:1], 0xe0
	s_load_dword s9, s[0:1], 0xe8
	s_add_u32 s6, s4, 0x1000
	s_addc_u32 s7, s5, 0
	s_add_u32 s8, s4, 0x1100
	s_waitcnt lgkmcnt(0)
	s_mul_i32 s24, s13, s12
	s_mul_i32 s24, s24, s9
	s_addc_u32 s9, s5, 0
	s_add_u32 s12, s4, 0x1200
	s_addc_u32 s13, s5, 0
	s_add_u32 s14, s4, 0x1300
	s_addc_u32 s15, s5, 0
	s_mov_b32 s25, 1
	v_mov_b32_e32 v17, 0
	s_branch .LBB0_2492
